# conv range-3 edge loops: same address-arithmetic trimming (loop-carried base + ds_read2 immediate offsets)
# baseline (speedup 1.0000x reference)
; template <int NQ, int NB, int L>
; __device__ __forceinline__ void conv_unit(LAS unsigned char* lds, const Args& a, int j, int seq0, int c, int tid) {
;     ...
;         const int dl_a = mw + 3 * GS - S_HI, dl_b = mw - S_LO;
;         static_assert(((3 * GS / 32) % 2 == 0) && (((S_HI - S_LO - 3 * GS) / 32 + 1) % 2 == 1), "conv step-count parity");
; #pragma unroll 1
;         for (int dl = d_lo; dl < dl_a; dl += 64) { CONV_STEP(Bc, Bn, dl, true); CONV_STEP(Bn, Bc, dl + 32, true); }
; #pragma unroll 1
;         for (int dl = dl_a; dl < dl_b; dl += 64) { CONV_STEP(Bc, Bn, dl, false); CONV_STEP(Bn, Bc, dl + 32, false); }
;         CONV_STEP(Bc, Bn, dl_b, false);
; #pragma unroll 1
;         for (int dl = dl_b + 32; dl <= d_hi; dl += 64) { CONV_STEP(Bn, Bc, dl, true); CONV_STEP(Bc, Bn, dl + 32, true); }
.LBB0_1341:
	s_waitcnt lgkmcnt(3)
	v_mfma_f32_16x16x32_bf16 v[60:63], v[70:73], v[82:85], v[90:93]
	s_mov_b32 s56, s71
	v_mfma_f32_16x16x32_bf16 v[64:67], v[74:77], v[82:85], v[86:89]
	s_waitcnt lgkmcnt(1)
	v_mfma_f32_16x16x32_bf16 v[34:37], v[78:81], v[24:27], v[36:39]
	v_mfma_f32_16x16x32_bf16 v[52:55], v[16:19], v[82:85], v[52:55]
	v_mfma_f32_16x16x32_bf16 v[56:59], v[78:81], v[82:85], v[94:97]
	v_mfma_f32_16x16x32_bf16 v[40:43], v[16:19], v[106:109], v[40:43]
	v_mfma_f32_16x16x32_bf16 v[28:31], v[78:81], v[106:109], v[28:31]
	v_mfma_f32_16x16x32_bf16 v[44:47], v[70:73], v[106:109], v[44:47]
	v_mfma_f32_16x16x32_bf16 v[48:51], v[74:77], v[106:109], v[48:51]
	ds_read_b128 v[82:85], v206 offset:8576
	ds_read_b128 v[106:109], v206 offset:8832
	ds_read_b128 v[130:133], v206 offset:9088
	ds_read_b128 v[148:151], v206 offset:9344
	v_mfma_f32_16x16x32_bf16 v[20:23], v[16:19], v[24:27], v[20:23]
	v_mfma_f32_16x16x32_bf16 v[102:105], v[70:73], v[24:27], v[102:105]
	v_mfma_f32_16x16x32_bf16 v[98:101], v[74:77], v[24:27], v[98:101]
	s_waitcnt lgkmcnt(4)
	v_mfma_f32_16x16x32_bf16 v[24:27], v[16:19], v[110:113], v[114:117]
	ds_read2_b32 v[16:17], v205 offset0:24 offset1:25
	ds_read2_b32 v[68:69], v205 offset0:25 offset1:26
	ds_read2_b32 v[18:19], v205 offset0:27 offset1:28
	ds_read2_b32 v[86:87], v205 offset0:16 offset1:17
	ds_read2_b32 v[88:89], v205 offset0:17 offset1:18
	ds_read2_b32 v[90:91], v205 offset0:19 offset1:20
	v_mfma_f32_16x16x32_bf16 v[78:81], v[78:81], v[110:113], v[118:121]
	v_mfma_f32_16x16x32_bf16 v[122:125], v[70:73], v[110:113], v[122:125]
	v_mfma_f32_16x16x32_bf16 v[126:129], v[74:77], v[110:113], v[126:129]
	s_waitcnt lgkmcnt(3)
	v_alignbit_b32 v19, v19, v18, v15
	v_alignbit_b32 v18, v18, v69, v14
	v_alignbit_b32 v17, v69, v17, v13
	v_alignbit_b32 v16, v68, v16, v12
	v_mfma_f32_16x16x32_bf16 v[118:121], v[74:77], v[148:151], v[78:81]
	s_waitcnt lgkmcnt(0)
	s_nop 1
	v_alignbit_b32 v81, v91, v90, v15
	v_alignbit_b32 v80, v90, v89, v14
	v_alignbit_b32 v79, v89, v87, v13
	v_alignbit_b32 v78, v88, v86, v12
	v_mfma_f32_16x16x32_bf16 v[94:97], v[74:77], v[82:85], v[56:59]
	v_mfma_f32_16x16x32_bf16 v[36:39], v[74:77], v[130:133], v[34:37]
	v_mfma_f32_16x16x32_bf16 v[90:93], v[16:19], v[82:85], v[60:63]
	v_mfma_f32_16x16x32_bf16 v[86:89], v[78:81], v[82:85], v[64:67]
	v_mfma_f32_16x16x32_bf16 v[52:55], v[70:73], v[82:85], v[52:55]
	ds_read_b128 v[82:85], v206 offset:8512
	v_mfma_f32_16x16x32_bf16 v[40:43], v[70:73], v[106:109], v[40:43]
	v_mfma_f32_16x16x32_bf16 v[28:31], v[74:77], v[106:109], v[28:31]
	v_mfma_f32_16x16x32_bf16 v[114:117], v[70:73], v[148:151], v[24:27]
	v_mfma_f32_16x16x32_bf16 v[44:47], v[16:19], v[106:109], v[44:47]
	v_mfma_f32_16x16x32_bf16 v[48:51], v[78:81], v[106:109], v[48:51]
	ds_read_b128 v[106:109], v206 offset:8768
	ds_read_b128 v[24:27], v206 offset:9024
	ds_read_b128 v[110:113], v206 offset:9280
	ds_read2_b32 v[34:35], v205 offset0:8 offset1:9
	ds_read2_b32 v[56:57], v205 offset0:9 offset1:10
	ds_read2_b32 v[58:59], v205 offset0:11 offset1:12
	ds_read2_b32 v[60:61], v205 offset0:0 offset1:1
	ds_read2_b32 v[62:63], v205 offset0:1 offset1:2
	ds_read2_b32 v[64:65], v205 offset0:3 offset1:4
	v_mfma_f32_16x16x32_bf16 v[20:23], v[70:73], v[130:133], v[20:23]
	s_waitcnt lgkmcnt(4)
	v_alignbit_b32 v71, v57, v35, v13
	s_waitcnt lgkmcnt(3)
	v_alignbit_b32 v73, v59, v58, v15
	v_mfma_f32_16x16x32_bf16 v[102:105], v[16:19], v[130:133], v[102:105]
	v_alignbit_b32 v72, v58, v57, v14
	v_alignbit_b32 v70, v56, v34, v12
	v_mfma_f32_16x16x32_bf16 v[98:101], v[78:81], v[130:133], v[98:101]
	v_mfma_f32_16x16x32_bf16 v[122:125], v[16:19], v[148:151], v[122:125]
	v_mfma_f32_16x16x32_bf16 v[126:129], v[78:81], v[148:151], v[126:129]
	s_add_i32 s94, s94, 64
	s_addk_i32 s71, 0xff80
	s_waitcnt lgkmcnt(0)
	v_alignbit_b32 v77, v65, v64, v15
	v_alignbit_b32 v76, v64, v63, v14
	v_alignbit_b32 v75, v63, v61, v13
	v_alignbit_b32 v74, v62, v60, v12
	v_add_u32_e32 v206, 0xffffff80, v206
	s_cmp_gt_i32 s94, s50
	v_add_u32_e32 v205, 0xffffff80, v205
	s_cbranch_scc0 .LBB0_1341
	v_sub_u32_e32 v134, v206, v194
	v_mfma_f32_16x16x32_bf16 v[66:69], v[16:19], v[82:85], v[52:55]
	v_add_u32_e32 v32, s75, v193
	v_mfma_f32_16x16x32_bf16 v[54:57], v[70:73], v[106:109], v[44:47]
	v_mfma_f32_16x16x32_bf16 v[50:53], v[74:77], v[106:109], v[48:51]
	v_mfma_f32_16x16x32_bf16 v[46:49], v[16:19], v[24:27], v[20:23]
	s_nop 2
	v_add_u32_e32 v20, v134, v194
	v_add_u32_e32 v21, s83, v193
	v_mfma_f32_16x16x32_bf16 v[62:65], v[16:19], v[106:109], v[40:43]
	v_mfma_f32_16x16x32_bf16 v[58:61], v[78:81], v[106:109], v[28:31]
	v_mfma_f32_16x16x32_bf16 v[42:45], v[78:81], v[24:27], v[36:39]
	v_mfma_f32_16x16x32_bf16 v[34:37], v[70:73], v[24:27], v[102:105]
	v_mfma_f32_16x16x32_bf16 v[24:27], v[74:77], v[24:27], v[98:101]
	ds_read_b128 v[130:133], v20 offset:8832
	s_nop 1
	ds_read_b128 v[98:101], v20 offset:9088
	v_mfma_f32_16x16x32_bf16 v[38:41], v[16:19], v[110:113], v[114:117]
	ds_read2_b32 v[16:17], v21 offset0:1 offset1:2
	ds_read2_b32 v[18:19], v21 offset0:3 offset1:4
	ds_read2_b32 v[106:107], v32 offset1:1
	ds_read2_b32 v[102:103], v21 offset1:1
	ds_read_b128 v[114:117], v20 offset:9344
	s_waitcnt lgkmcnt(3)
	v_alignbit_b32 v105, v19, v18, v15
	v_mfma_f32_16x16x32_bf16 v[28:31], v[78:81], v[110:113], v[118:121]
	s_nop 2
	ds_read2_b32 v[118:119], v32 offset0:1 offset1:2
	ds_read2_b32 v[108:109], v32 offset0:3 offset1:4
	v_alignbit_b32 v104, v18, v17, v14
	s_waitcnt lgkmcnt(3)
	v_alignbit_b32 v103, v17, v103, v13
	v_mfma_f32_16x16x32_bf16 v[20:23], v[70:73], v[110:113], v[122:125]
	v_alignbit_b32 v102, v16, v102, v12
	v_mfma_f32_16x16x32_bf16 v[16:19], v[74:77], v[110:113], v[126:129]
	s_waitcnt lgkmcnt(0)
	v_alignbit_b32 v109, v109, v108, v15
	v_alignbit_b32 v108, v108, v119, v14
	v_alignbit_b32 v107, v119, v107, v13
	v_alignbit_b32 v106, v118, v106, v12
	v_mov_b64_e32 v[112:113], v[72:73]
	v_mov_b64_e32 v[120:121], v[76:77]
	s_movk_i32 s71, 0xc0
	v_mov_b32_e32 v32, v216
	v_add_u32_e32 v207, 0x1523e, v216
	s_mov_b32 s94, s92
	v_mov_b64_e32 v[110:111], v[70:71]
	v_mov_b64_e32 v[118:119], v[74:75]
	s_branch .LBB0_1344
; template <int NQ, int NB, int L>
; __device__ __forceinline__ void conv_unit(LAS unsigned char* lds, const Args& a, int j, int seq0, int c, int tid) {
;     ...
;         for (int dl = dl_b + 32; dl <= d_hi; dl += 64) { CONV_STEP(Bn, Bc, dl, true); CONV_STEP(Bc, Bn, dl + 32, true); }
.LBB0_1343:
	s_waitcnt lgkmcnt(9)
	v_mfma_f32_16x16x32_bf16 v[38:41], v[106:109], v[122:125], v[38:41]
	v_mfma_f32_16x16x32_bf16 v[28:31], v[102:105], v[122:125], v[28:31]
	v_mfma_f32_16x16x32_bf16 v[20:23], v[110:113], v[122:125], v[20:23]
	v_mfma_f32_16x16x32_bf16 v[16:19], v[118:121], v[122:125], v[16:19]
	s_setprio 0
	s_addk_i32 s56, 0xff80
	s_add_i32 s94, s94, 64
	s_sub_i32 s71, s71, 64
	s_waitcnt lgkmcnt(7)
	v_alignbit_b32 v109, v187, v186, v15
	v_alignbit_b32 v108, v186, v183, v14
	s_waitcnt lgkmcnt(1)
	v_alignbit_b32 v107, v183, v189, v13
	v_alignbit_b32 v106, v182, v188, v12
	v_alignbit_b32 v105, v181, v180, v15
	v_alignbit_b32 v104, v180, v173, v14
	v_alignbit_b32 v103, v173, v169, v13
	v_alignbit_b32 v102, v172, v168, v12
	s_cmp_gt_i32 s94, s86
	v_add_u32_e32 v207, 0xffffff80, v207
	s_cbranch_scc1 .LBB0_1352
.LBB0_1344:
	ds_read2_b32 v[174:175], v207 offset0:24 offset1:25
	ds_read2_b32 v[176:177], v207 offset0:25 offset1:26
	ds_read2_b32 v[184:185], v207 offset0:27 offset1:28
	ds_read2_b32 v[166:167], v207 offset0:16 offset1:17
	v_add_u32_e32 v241, s56, v201
	ds_read2_b32 v[170:171], v207 offset0:17 offset1:18
	ds_read2_b32 v[178:179], v207 offset0:19 offset1:20
	ds_read_b128 v[134:137], v241 offset:64
	ds_read_b128 v[126:129], v241 offset:320
	ds_read_b128 v[122:125], v241 offset:576
	s_setprio 1
	s_add_i32 s95, s71, 0xffffffa0
	s_cmpk_gt_u32 s95, 0x1040
	s_cbranch_scc1 .LBB0_1346
	v_mfma_f32_16x16x32_bf16 v[62:65], v[110:113], v[130:133], v[62:65]
	v_mfma_f32_16x16x32_bf16 v[58:61], v[118:121], v[130:133], v[58:61]
	v_mfma_f32_16x16x32_bf16 v[54:57], v[106:109], v[130:133], v[54:57]
	v_mfma_f32_16x16x32_bf16 v[50:53], v[102:105], v[130:133], v[50:53]

; template <int NQ, int NB, int L>
; __device__ __forceinline__ void conv_unit(LAS unsigned char* lds, const Args& a, int j, int seq0, int c, int tid) {
;     ...
;         for (int dl = dl_b + 32; dl <= d_hi; dl += 64) { CONV_STEP(Bn, Bc, dl, true); CONV_STEP(Bc, Bn, dl + 32, true); }
.LBB0_1348:
	s_waitcnt lgkmcnt(9)
	v_mfma_f32_16x16x32_bf16 v[38:41], v[110:113], v[114:117], v[38:41]
	v_mfma_f32_16x16x32_bf16 v[28:31], v[118:121], v[114:117], v[28:31]
	v_mfma_f32_16x16x32_bf16 v[20:23], v[106:109], v[114:117], v[20:23]
	v_mfma_f32_16x16x32_bf16 v[16:19], v[102:105], v[114:117], v[16:19]
	s_setprio 0
	ds_read2_b32 v[182:183], v207 offset0:9 offset1:10
	ds_read2_b32 v[186:187], v207 offset0:11 offset1:12
	ds_read2_b32 v[168:169], v207 offset0:0 offset1:1
	ds_read2_b32 v[172:173], v207 offset0:1 offset1:2
	ds_read2_b32 v[180:181], v207 offset0:3 offset1:4
	ds_read_b128 v[130:133], v241
	ds_read_b128 v[98:101], v241 offset:256
	ds_read2_b32 v[188:189], v207 offset0:8 offset1:9
	ds_read_b128 v[114:117], v241 offset:512
	s_waitcnt lgkmcnt(14)
	v_alignbit_b32 v113, v185, v184, v15
	v_alignbit_b32 v112, v184, v177, v14
	v_alignbit_b32 v111, v177, v175, v13
	v_alignbit_b32 v110, v176, v174, v12
	s_waitcnt lgkmcnt(12)
	v_alignbit_b32 v121, v179, v178, v15
	v_alignbit_b32 v120, v178, v171, v14
	v_alignbit_b32 v119, v171, v167, v13
	v_alignbit_b32 v118, v170, v166, v12
	s_setprio 1
	s_add_i32 s95, s71, 0xffffff80
	s_cmpk_gt_u32 s95, 0x1040
	s_cbranch_scc1 .LBB0_1350
	s_waitcnt lgkmcnt(11)
	v_mfma_f32_16x16x32_bf16 v[62:65], v[106:109], v[134:137], v[62:65]
	v_mfma_f32_16x16x32_bf16 v[58:61], v[102:105], v[134:137], v[58:61]
	v_mfma_f32_16x16x32_bf16 v[54:57], v[110:113], v[134:137], v[54:57]
	v_mfma_f32_16x16x32_bf16 v[50:53], v[118:121], v[134:137], v[50:53]

; template <int NQ, int NB, int L>
; __device__ __forceinline__ void conv_unit(LAS unsigned char* lds, const Args& a, int j, int seq0, int c, int tid) {
;     ...
;         const int dl_a = mw + 3 * GS - S_HI, dl_b = mw - S_LO;
;         static_assert(((3 * GS / 32) % 2 == 0) && (((S_HI - S_LO - 3 * GS) / 32 + 1) % 2 == 1), "conv step-count parity");
; #pragma unroll 1
;         for (int dl = d_lo; dl < dl_a; dl += 64) { CONV_STEP(Bc, Bn, dl, true); CONV_STEP(Bn, Bc, dl + 32, true); }
; #pragma unroll 1
;         for (int dl = dl_a; dl < dl_b; dl += 64) { CONV_STEP(Bc, Bn, dl, false); CONV_STEP(Bn, Bc, dl + 32, false); }
;         CONV_STEP(Bc, Bn, dl_b, false);
; #pragma unroll 1
;         for (int dl = dl_b + 32; dl <= d_hi; dl += 64) { CONV_STEP(Bn, Bc, dl, true); CONV_STEP(Bc, Bn, dl + 32, true); }
.LBB0_1546:
	s_waitcnt lgkmcnt(3)
	v_mfma_f32_16x16x32_bf16 v[68:71], v[78:81], v[90:93], v[94:97]
	s_waitcnt lgkmcnt(1)
	v_mfma_f32_16x16x32_bf16 v[28:31], v[24:27], v[36:39], v[28:31]
	v_mfma_f32_16x16x32_bf16 v[44:47], v[86:89], v[36:39], v[44:47]
	s_mov_b32 s49, s56
	v_mfma_f32_16x16x32_bf16 v[110:113], v[78:81], v[36:39], v[110:113]
	v_mfma_f32_16x16x32_bf16 v[106:109], v[82:85], v[36:39], v[106:109]
	v_mfma_f32_16x16x32_bf16 v[60:63], v[24:27], v[90:93], v[60:63]
	v_mfma_f32_16x16x32_bf16 v[64:67], v[86:89], v[90:93], v[102:105]
	v_mfma_f32_16x16x32_bf16 v[72:75], v[82:85], v[90:93], v[98:101]
	v_mfma_f32_16x16x32_bf16 v[48:51], v[24:27], v[114:117], v[48:51]
	v_mfma_f32_16x16x32_bf16 v[40:43], v[86:89], v[114:117], v[40:43]
	v_mfma_f32_16x16x32_bf16 v[52:55], v[78:81], v[114:117], v[52:55]
	v_mfma_f32_16x16x32_bf16 v[56:59], v[82:85], v[114:117], v[56:59]
	ds_read_b128 v[90:93], v206 offset:16768
	ds_read_b128 v[114:117], v206 offset:17280
	ds_read_b128 v[138:141], v206 offset:17792
	ds_read_b128 v[178:181], v206 offset:18304
	s_waitcnt lgkmcnt(4)
	v_mfma_f32_16x16x32_bf16 v[34:37], v[24:27], v[118:121], v[122:125]
	ds_read2_b32 v[24:25], v205 offset0:24 offset1:25
	ds_read2_b32 v[38:39], v205 offset0:25 offset1:26
	ds_read2_b32 v[26:27], v205 offset0:27 offset1:28
	ds_read2_b32 v[76:77], v205 offset0:16 offset1:17
	ds_read2_b32 v[98:99], v205 offset0:17 offset1:18
	ds_read2_b32 v[94:95], v205 offset0:19 offset1:20
	v_mfma_f32_16x16x32_bf16 v[86:89], v[86:89], v[118:121], v[126:129]
	v_mfma_f32_16x16x32_bf16 v[130:133], v[78:81], v[118:121], v[130:133]
	v_mfma_f32_16x16x32_bf16 v[134:137], v[82:85], v[118:121], v[134:137]
	s_waitcnt lgkmcnt(3)
	v_alignbit_b32 v27, v27, v26, v23
	v_alignbit_b32 v26, v26, v39, v22
	v_alignbit_b32 v25, v39, v25, v21
	v_alignbit_b32 v24, v38, v24, v20
	v_mfma_f32_16x16x32_bf16 v[126:129], v[82:85], v[178:181], v[86:89]
	s_waitcnt lgkmcnt(0)
	s_nop 1
	v_alignbit_b32 v89, v95, v94, v23
	v_alignbit_b32 v88, v94, v99, v22
	v_alignbit_b32 v87, v99, v77, v21
	v_alignbit_b32 v86, v98, v76, v20
	v_mfma_f32_16x16x32_bf16 v[102:105], v[82:85], v[90:93], v[64:67]
	v_mfma_f32_16x16x32_bf16 v[122:125], v[78:81], v[178:181], v[34:37]
	v_mfma_f32_16x16x32_bf16 v[94:97], v[24:27], v[90:93], v[68:71]
	v_mfma_f32_16x16x32_bf16 v[98:101], v[86:89], v[90:93], v[72:75]
	v_mfma_f32_16x16x32_bf16 v[60:63], v[78:81], v[90:93], v[60:63]
	ds_read_b128 v[90:93], v206 offset:16704
	v_mfma_f32_16x16x32_bf16 v[48:51], v[78:81], v[114:117], v[48:51]
	v_mfma_f32_16x16x32_bf16 v[40:43], v[82:85], v[114:117], v[40:43]
	v_mfma_f32_16x16x32_bf16 v[52:55], v[24:27], v[114:117], v[52:55]
	v_mfma_f32_16x16x32_bf16 v[56:59], v[86:89], v[114:117], v[56:59]
	ds_read_b128 v[114:117], v206 offset:17216
	ds_read_b128 v[36:39], v206 offset:17728
	ds_read_b128 v[118:121], v206 offset:18240
	ds_read2_b32 v[34:35], v205 offset0:8 offset1:9
	ds_read2_b32 v[64:65], v205 offset0:9 offset1:10
	ds_read2_b32 v[66:67], v205 offset0:11 offset1:12
	ds_read2_b32 v[68:69], v205 offset0:0 offset1:1
	ds_read2_b32 v[70:71], v205 offset0:1 offset1:2
	ds_read2_b32 v[72:73], v205 offset0:3 offset1:4
	v_mfma_f32_16x16x32_bf16 v[28:31], v[78:81], v[138:141], v[28:31]
	s_waitcnt lgkmcnt(4)
	v_alignbit_b32 v79, v65, v35, v21
	s_waitcnt lgkmcnt(3)
	v_alignbit_b32 v81, v67, v66, v23
	v_mfma_f32_16x16x32_bf16 v[44:47], v[82:85], v[138:141], v[44:47]
	v_alignbit_b32 v80, v66, v65, v22
	v_alignbit_b32 v78, v64, v34, v20
	v_mfma_f32_16x16x32_bf16 v[110:113], v[24:27], v[138:141], v[110:113]
	v_mfma_f32_16x16x32_bf16 v[106:109], v[86:89], v[138:141], v[106:109]
	v_mfma_f32_16x16x32_bf16 v[130:133], v[24:27], v[178:181], v[130:133]
	v_mfma_f32_16x16x32_bf16 v[134:137], v[86:89], v[178:181], v[134:137]
	s_add_i32 vcc_lo, vcc_lo, 64
	s_addk_i32 s56, 0xff80
	s_waitcnt lgkmcnt(0)
	v_alignbit_b32 v85, v73, v72, v23
	v_alignbit_b32 v84, v72, v71, v22
	v_alignbit_b32 v83, v71, v69, v21
	v_alignbit_b32 v82, v70, v68, v20
	v_add_u32_e32 v206, 0xffffff80, v206
	s_cmp_ge_i32 vcc_lo, s51
	v_add_u32_e32 v205, 0xffffff80, v205
	s_cbranch_scc0 .LBB0_1546
	v_sub_u32_e32 v142, v206, v217
	v_mfma_f32_16x16x32_bf16 v[74:77], v[24:27], v[90:93], v[60:63]
	v_add_u32_e32 v32, s97, v216
	v_mfma_f32_16x16x32_bf16 v[62:65], v[78:81], v[114:117], v[52:55]
	v_mfma_f32_16x16x32_bf16 v[58:61], v[82:85], v[114:117], v[56:59]
	v_mfma_f32_16x16x32_bf16 v[54:57], v[24:27], v[36:39], v[28:31]
	s_nop 2
	v_add_u32_e32 v28, v142, v217
	v_add_u32_e32 v29, s50, v216
	v_mfma_f32_16x16x32_bf16 v[70:73], v[24:27], v[114:117], v[48:51]
	v_mfma_f32_16x16x32_bf16 v[66:69], v[86:89], v[114:117], v[40:43]
	v_mfma_f32_16x16x32_bf16 v[50:53], v[86:89], v[36:39], v[44:47]
	v_mfma_f32_16x16x32_bf16 v[42:45], v[78:81], v[36:39], v[110:113]
	v_mfma_f32_16x16x32_bf16 v[34:37], v[82:85], v[36:39], v[106:109]
	ds_read_b128 v[138:141], v28 offset:17280
	s_nop 1
	ds_read_b128 v[106:109], v28 offset:17792
	v_mfma_f32_16x16x32_bf16 v[46:49], v[24:27], v[118:121], v[122:125]
	ds_read2_b32 v[24:25], v29 offset0:1 offset1:2
	ds_read2_b32 v[26:27], v29 offset0:3 offset1:4
	ds_read2_b32 v[114:115], v32 offset1:1
	ds_read2_b32 v[110:111], v29 offset1:1
	ds_read_b128 v[122:125], v28 offset:18304
	s_waitcnt lgkmcnt(3)
	v_alignbit_b32 v113, v27, v26, v23
	v_mfma_f32_16x16x32_bf16 v[38:41], v[86:89], v[118:121], v[126:129]
	s_nop 2
	ds_read2_b32 v[126:127], v32 offset0:1 offset1:2
	ds_read2_b32 v[116:117], v32 offset0:3 offset1:4
	v_alignbit_b32 v112, v26, v25, v22
	s_waitcnt lgkmcnt(3)
	v_alignbit_b32 v111, v25, v111, v21
	v_mfma_f32_16x16x32_bf16 v[28:31], v[78:81], v[118:121], v[130:133]
	v_alignbit_b32 v110, v24, v110, v20
	v_mfma_f32_16x16x32_bf16 v[24:27], v[82:85], v[118:121], v[134:137]
	s_waitcnt lgkmcnt(0)
	v_alignbit_b32 v117, v117, v116, v23
	v_alignbit_b32 v116, v116, v127, v22
	v_alignbit_b32 v115, v127, v115, v21
	v_alignbit_b32 v114, v126, v114, v20
	v_mov_b64_e32 v[120:121], v[80:81]
	v_mov_b64_e32 v[128:129], v[84:85]
	s_movk_i32 s56, 0x1c0
	v_mov_b32_e32 v32, v225
	v_add_u32_e32 v207, 0x1713e, v225
	s_mov_b32 vcc_lo, s91
	v_mov_b64_e32 v[118:119], v[78:79]
	v_mov_b64_e32 v[126:127], v[82:83]
	s_branch .LBB0_1549
; template <int NQ, int NB, int L>
; __device__ __forceinline__ void conv_unit(LAS unsigned char* lds, const Args& a, int j, int seq0, int c, int tid) {
;     ...
;         for (int dl = dl_b + 32; dl <= d_hi; dl += 64) { CONV_STEP(Bn, Bc, dl, true); CONV_STEP(Bc, Bn, dl + 32, true); }
.LBB0_1548:
	s_waitcnt lgkmcnt(9)
	v_mfma_f32_16x16x32_bf16 v[46:49], v[114:117], v[130:133], v[46:49]
	v_mfma_f32_16x16x32_bf16 v[38:41], v[110:113], v[130:133], v[38:41]
	v_mfma_f32_16x16x32_bf16 v[28:31], v[118:121], v[130:133], v[28:31]
	v_mfma_f32_16x16x32_bf16 v[24:27], v[126:129], v[130:133], v[24:27]
	s_setprio 0
	s_addk_i32 s49, 0xff80
	s_add_i32 vcc_lo, vcc_lo, 64
	s_sub_i32 s56, s56, 64
	s_waitcnt lgkmcnt(7)
	v_alignbit_b32 v117, v199, v198, v23
	v_alignbit_b32 v116, v198, v195, v22
	s_waitcnt lgkmcnt(1)
	v_alignbit_b32 v115, v195, v201, v21
	v_alignbit_b32 v114, v194, v200, v20
	v_alignbit_b32 v113, v193, v192, v23
	v_alignbit_b32 v112, v192, v185, v22
	v_alignbit_b32 v111, v185, v181, v21
	v_alignbit_b32 v110, v184, v180, v20
	s_cmp_gt_i32 vcc_lo, s83
	v_add_u32_e32 v207, 0xffffff80, v207
	s_cbranch_scc1 .LBB0_1557
.LBB0_1549:
	ds_read2_b32 v[186:187], v207 offset0:24 offset1:25
	ds_read2_b32 v[188:189], v207 offset0:25 offset1:26
	ds_read2_b32 v[196:197], v207 offset0:27 offset1:28
	ds_read2_b32 v[178:179], v207 offset0:16 offset1:17
	v_add_u32_e32 v252, s49, v224
	ds_read2_b32 v[182:183], v207 offset0:17 offset1:18
	ds_read2_b32 v[190:191], v207 offset0:19 offset1:20
	ds_read_b128 v[142:145], v252 offset:64
	ds_read_b128 v[134:137], v252 offset:576
	ds_read_b128 v[130:133], v252 offset:1088
	s_setprio 1
	s_add_i32 vcc_hi, s56, 0xffffff20
	s_cmpk_gt_u32 vcc_hi, 0x20c0
	s_cbranch_scc1 .LBB0_1551
	v_mfma_f32_16x16x32_bf16 v[70:73], v[118:121], v[138:141], v[70:73]
	v_mfma_f32_16x16x32_bf16 v[66:69], v[126:129], v[138:141], v[66:69]
	v_mfma_f32_16x16x32_bf16 v[62:65], v[114:117], v[138:141], v[62:65]
	v_mfma_f32_16x16x32_bf16 v[58:61], v[110:113], v[138:141], v[58:61]

; template <int NQ, int NB, int L>
; __device__ __forceinline__ void conv_unit(LAS unsigned char* lds, const Args& a, int j, int seq0, int c, int tid) {
;     ...
;         for (int dl = dl_b + 32; dl <= d_hi; dl += 64) { CONV_STEP(Bn, Bc, dl, true); CONV_STEP(Bc, Bn, dl + 32, true); }
.LBB0_1553:
	s_waitcnt lgkmcnt(9)
	v_mfma_f32_16x16x32_bf16 v[46:49], v[118:121], v[122:125], v[46:49]
	v_mfma_f32_16x16x32_bf16 v[38:41], v[126:129], v[122:125], v[38:41]
	v_mfma_f32_16x16x32_bf16 v[28:31], v[114:117], v[122:125], v[28:31]
	v_mfma_f32_16x16x32_bf16 v[24:27], v[110:113], v[122:125], v[24:27]
	s_setprio 0
	ds_read2_b32 v[194:195], v207 offset0:9 offset1:10
	ds_read2_b32 v[198:199], v207 offset0:11 offset1:12
	ds_read2_b32 v[180:181], v207 offset0:0 offset1:1
	ds_read2_b32 v[184:185], v207 offset0:1 offset1:2
	ds_read2_b32 v[192:193], v207 offset0:3 offset1:4
	ds_read_b128 v[138:141], v252
	ds_read_b128 v[106:109], v252 offset:512
	ds_read2_b32 v[200:201], v207 offset0:8 offset1:9
	ds_read_b128 v[122:125], v252 offset:1024
	s_waitcnt lgkmcnt(14)
	v_alignbit_b32 v121, v197, v196, v23
	v_alignbit_b32 v120, v196, v189, v22
	v_alignbit_b32 v119, v189, v187, v21
	v_alignbit_b32 v118, v188, v186, v20
	s_waitcnt lgkmcnt(12)
	v_alignbit_b32 v129, v191, v190, v23
	v_alignbit_b32 v128, v190, v183, v22
	v_alignbit_b32 v127, v183, v179, v21
	v_alignbit_b32 v126, v182, v178, v20
	s_setprio 1
	s_add_i32 vcc_hi, s56, 0xffffff00
	s_cmpk_gt_u32 vcc_hi, 0x20c0
	s_cbranch_scc1 .LBB0_1555
	s_waitcnt lgkmcnt(11)
	v_mfma_f32_16x16x32_bf16 v[70:73], v[114:117], v[142:145], v[70:73]
	v_mfma_f32_16x16x32_bf16 v[66:69], v[110:113], v[142:145], v[66:69]
	v_mfma_f32_16x16x32_bf16 v[62:65], v[118:121], v[142:145], v[62:65]
	v_mfma_f32_16x16x32_bf16 v[58:61], v[126:129], v[142:145], v[58:61]
